# layer-1 w_in filler items re-partitioned: pre-P1 seam keeps 512 items, the P1 idle slot of workgroups 192..255 converts 2048 items
# speedup vs baseline: 1.0243x; 1.0065x over previous
; __global__ void __launch_bounds__(512, 2) mk_fwd(Args args) {
;     ...
;     if (IN(0) && IN(1)) { if (DEPTH == 2) { xcd_barrier_arrive(xbar); CONVERT_ITEMS(I_L, I_L + 1280); xcd_barrier_wait(xbar); } else xcd_barrier(xbar); }
.LBB0_160:
	s_or_b64 exec, exec, s[0:1]
	v_mov_b32_e32 v0, v252
	s_lshl_b32 s14, s96, 3
	v_readfirstlane_b32 s0, v0
	s_ashr_i32 s2, s0, 6
	s_add_i32 s3, s14, s2
	s_lshl_b32 s0, s86, 3
	s_add_i32 s15, s3, 0x1780
	v_writelane_b32 v253, s0, 34
	s_mov_b64 s[0:1], s[20:21]
	s_cmpk_gt_i32 s15, 0x197f
	s_cbranch_scc1 .LBB0_209
	s_add_u32 s24, s0, 0x200000
	s_addc_u32 s25, s1, 0
	s_add_u32 s26, s0, 0x3e00000
	s_addc_u32 s27, s1, 0
	s_add_u32 s28, s0, 0x4e00000
	s_addc_u32 s29, s1, 0
	s_add_u32 s30, s0, 0x5e00000
	s_addc_u32 s31, s1, 0
	s_add_u32 s34, s0, 0x10000
	s_addc_u32 s35, s1, 0
	v_and_b32_e32 v2, 63, v0
	v_bfe_u32 v80, v0, 4, 2
	v_bfe_u32 v82, v0, 3, 3
	v_lshlrev_b32_e32 v0, 3, v0
	s_add_u32 s37, s0, 0x14000
	s_mulk_i32 s2, 0x4100
	v_lshlrev_b32_e32 v68, 2, v2
	v_and_b32_e32 v0, 56, v0
	s_addc_u32 s38, s1, 0
	s_add_i32 s2, s2, 0
	v_and_b32_e32 v4, 60, v68
	v_mul_u32_u24_e32 v3, 0x104, v0
	v_lshlrev_b32_e32 v5, 2, v82
	v_readlane_b32 s40, v253, 18
	v_lshl_add_u32 v1, v4, 2, s2
	s_movk_i32 s0, 0x104
	v_add3_u32 v83, s2, v3, v5
	v_readlane_b32 s50, v253, 28
	v_readlane_b32 s51, v253, 29
	v_or_b32_e32 v3, 4, v80
	v_mov_b32_e32 v69, 0
	v_mad_u32_u24 v81, v80, s0, v1
	v_readlane_b32 s41, v253, 19
	v_readlane_b32 s42, v253, 20
	v_readlane_b32 s43, v253, 21
	v_readlane_b32 s44, v253, 22
	v_readlane_b32 s45, v253, 23
	v_readlane_b32 s46, v253, 24
	v_readlane_b32 s47, v253, 25
	v_readlane_b32 s48, v253, 26
	v_readlane_b32 s49, v253, 27
	v_readlane_b32 s52, v253, 30
	v_readlane_b32 s53, v253, 31
	v_readlane_b32 s54, v253, 32
	v_readlane_b32 s55, v253, 33
	s_cmp_lg_u64 s[50:51], 0
	v_mul_u32_u24_e32 v3, 0x104, v3
	v_or_b32_e32 v84, 8, v82
	v_or_b32_e32 v85, 16, v82
	v_or_b32_e32 v86, 24, v82
	v_or_b32_e32 v87, 32, v82
	v_or_b32_e32 v88, 40, v82
	v_or_b32_e32 v89, 48, v82
	v_or_b32_e32 v90, 56, v82
	s_cselect_b64 s[0:1], -1, 0
	v_add_u32_e32 v91, s2, v68
	v_lshl_add_u64 v[70:71], s[16:17], 0, v[68:69]
	s_mov_b32 s39, 0x8000
	s_mov_b32 s40, 0x10000
	s_mov_b32 s41, 0x18000
	s_mov_b32 s42, 0x20000
	s_mov_b32 s43, 0x28000
	s_mov_b32 s44, 0x30000
	s_mov_b32 s45, 0x38000
	s_mov_b32 s46, 0x40000
	s_mov_b32 s47, 0x48000
	s_mov_b32 s48, 0x50000
	s_mov_b32 s49, 0x58000
	s_mov_b32 s50, 0x60000
	s_mov_b32 s51, 0x68000
	s_mov_b32 s52, 0x70000
	s_mov_b32 s53, 0x78000
	v_add_u32_e32 v92, 0x410, v81
	v_add_u32_e32 v93, 0x418, v81
	v_add_u32_e32 v94, 0x820, v81
	v_add_u32_e32 v95, 0x828, v81
	v_add_u32_e32 v96, 0xc30, v81
	v_add_u32_e32 v97, 0xc38, v81
	v_add_u32_e32 v98, 0x1040, v81
	v_add_u32_e32 v99, 0x1048, v81
	v_add_u32_e32 v100, 0x1450, v81
	v_add_u32_e32 v101, 0x1458, v81
	v_add_u32_e32 v102, 0x1860, v81
	v_add_u32_e32 v103, 0x1868, v81
	v_add_u32_e32 v104, 0x1c70, v81
	v_add_u32_e32 v105, 0x1c78, v81
	v_add_u32_e32 v106, 0x2080, v81
	v_add_u32_e32 v107, 0x2088, v81
	v_add_u32_e32 v108, 0x2490, v81
	v_add_u32_e32 v109, 0x2498, v81
	v_add_u32_e32 v110, 0x28a0, v81
	v_add_u32_e32 v111, 0x28a8, v81
	v_add_u32_e32 v112, 0x2cb0, v81
	v_add_u32_e32 v113, 0x2cb8, v81
	v_add_u32_e32 v114, 0x30c0, v81
	v_add_u32_e32 v115, 0x30c8, v81
	v_add_u32_e32 v116, 0x34d0, v81
	v_add_u32_e32 v117, 0x34d8, v81
	v_add_u32_e32 v118, 0x38e0, v81
	v_add_u32_e32 v119, 0x38e8, v81
	v_add_u32_e32 v120, 0x3cf0, v81
	v_lshlrev_b32_e32 v72, 2, v2
	s_mov_b32 s54, 0xf0000
	s_mov_b32 s55, 0x10e000
	s_mov_b32 s56, 0x12c000
	s_mov_b32 s57, 0x14a000
	s_mov_b32 s58, 0x168000
	s_mov_b32 s59, 0x186000
	s_mov_b32 s60, 0x1a4000
	s_mov_b32 s61, 0x1c2000
	v_lshlrev_b32_e32 v68, 2, v4
	v_add_u32_e32 v121, 0x3cf8, v81
	v_lshlrev_b32_e32 v74, 1, v0
	v_add_u32_e32 v122, v1, v3
	s_branch .LBB0_163
.LBB0_162:
	v_readlane_b32 s2, v253, 34
	s_add_i32 s15, s15, s2
	s_cmpk_gt_i32 s15, 0x197f
	s_cbranch_scc1 .LBB0_209

.LBB0_427:
	s_or_b64 exec, exec, s[0:1]
	v_mov_b32_e32 v0, v252
	v_readlane_b32 s3, v254, 33
	v_readfirstlane_b32 s0, v0
	s_ashr_i32 s2, s0, 6
	s_add_i32 s26, s3, s2
	s_cmpk_lg_i32 s86, 0x100
	s_cbranch_scc1 .Lseam1_init_done
	s_sub_i32 s3, s96, 0xc0
	s_lshl_b32 s26, s3, 3
	s_add_i32 s26, s26, s2
	s_addk_i32 s26, 0x1980
	s_cmp_lt_i32 s3, 0
	s_cselect_b32 s26, 0x2180, s26
